# sel: half-1 first key tiles prefetched during half-0 transposes; queue result parked in SGPR
# speedup vs baseline: 1.0141x; 1.0023x over previous
.LBB0_826:
	s_lshl_b32 s6, s12, 14
	v_and_b32_e32 v99, 63, v106
	s_add_i32 s6, s6, 0
	s_waitcnt vmcnt(0)
	v_readfirstlane_b32 s101, v240
	s_cmpk_lt_u32 s19, 0x1001
	s_cbranch_scc1 .Lselpf2_skip
	s_min_u32 s98, s19, 0x2000
	s_addk_i32 s98, 0xf01f
	s_lshr_b32 s98, s98, 5
	s_sub_i32 s98, s98, s12
	s_cmp_lt_i32 s98, 1
	s_cbranch_scc1 .Lselpf2_skip
	s_add_i32 s99, s98, 7
	s_lshr_b32 s100, s99, 29
	s_add_i32 s99, s99, s100
	s_ashr_i32 s99, s99, 3
	s_add_i32 s99, s99, -1
	s_lshl_b32 s99, s99, 3
	s_add_i32 s100, s12, 0x80
	s_min_u32 s98, s99, 8
	s_add_i32 s98, s98, s100
	s_min_u32 s99, s99, 16
	s_add_i32 s99, s99, s100
	v_lshl_or_b32 v220, s100, 5, v191
	v_lshl_or_b32 v236, s98, 5, v191
	v_lshl_or_b32 v252, s99, 5, v191
	v_lshlrev_b32_e32 v220, 7, v220
	v_lshlrev_b32_e32 v236, 7, v236
	v_lshlrev_b32_e32 v252, 7, v252
	v_mov_b32_e32 v221, 0
	v_mov_b32_e32 v237, 0
	v_mov_b32_e32 v253, 0
	v_lshl_add_u64 v[220:221], v[100:101], 0, v[220:221]
	v_lshl_add_u64 v[236:237], v[100:101], 0, v[236:237]
	v_lshl_add_u64 v[252:253], v[100:101], 0, v[252:253]
	global_load_dwordx4 v[208:211], v[220:221], off
	global_load_dwordx4 v[212:215], v[220:221], off offset:1024
	global_load_dwordx4 v[216:219], v[220:221], off offset:2048
	global_load_dwordx4 v[220:223], v[220:221], off offset:3072
	global_load_dwordx4 v[224:227], v[236:237], off
	global_load_dwordx4 v[228:231], v[236:237], off offset:1024
	global_load_dwordx4 v[232:235], v[236:237], off offset:2048
	global_load_dwordx4 v[236:239], v[236:237], off offset:3072
	global_load_dwordx4 v[240:243], v[252:253], off
	global_load_dwordx4 v[244:247], v[252:253], off offset:1024
	global_load_dwordx4 v[248:251], v[252:253], off offset:2048
	global_load_dwordx4 v[252:255], v[252:253], off offset:3072
.Lselpf2_skip:
	s_cmpk_lt_u32 s19, 0x101
	v_lshl_add_u32 v190, v99, 2, s6
	s_waitcnt lgkmcnt(0)
	s_barrier
	s_cbranch_scc1 .LBB0_830
	s_waitcnt vmcnt(12)
	ds_read2st64_b32 v[62:63], v190 offset1:1
	ds_read2st64_b32 v[60:61], v190 offset0:2 offset1:3
	ds_read2st64_b32 v[58:59], v190 offset0:4 offset1:5
	ds_read2st64_b32 v[56:57], v190 offset0:6 offset1:7
	s_waitcnt vmcnt(0)
	ds_read2st64_b32 v[54:55], v190 offset0:8 offset1:9
	ds_read2st64_b32 v[52:53], v190 offset0:10 offset1:11
	ds_read2st64_b32 v[50:51], v190 offset0:12 offset1:13
	ds_read2st64_b32 v[48:49], v190 offset0:14 offset1:15
	ds_read2st64_b32 v[46:47], v190 offset0:16 offset1:17
	ds_read2st64_b32 v[44:45], v190 offset0:18 offset1:19
	ds_read2st64_b32 v[42:43], v190 offset0:20 offset1:21
	ds_read2st64_b32 v[40:41], v190 offset0:22 offset1:23
	ds_read2st64_b32 v[38:39], v190 offset0:24 offset1:25
	ds_read2st64_b32 v[36:37], v190 offset0:26 offset1:27
	ds_read2st64_b32 v[34:35], v190 offset0:28 offset1:29
	ds_read2st64_b32 v[32:33], v190 offset0:30 offset1:31
	v_mov_b32_e32 v186, 0
	s_cmpk_lt_u32 s19, 0x801
	v_mov_b32_e32 v185, 0
	v_mov_b32_e32 v183, 0
	v_mov_b32_e32 v161, 0
	v_mov_b32_e32 v159, 0
	v_mov_b32_e32 v157, 0
	v_mov_b32_e32 v155, 0
	v_mov_b32_e32 v153, 0
	v_mov_b32_e32 v151, 0
	v_mov_b32_e32 v149, 0
	v_mov_b32_e32 v147, 0
	v_mov_b32_e32 v145, 0
	v_mov_b32_e32 v143, 0
	v_mov_b32_e32 v141, 0
	v_mov_b32_e32 v139, 0
	v_mov_b32_e32 v137, 0
	v_mov_b32_e32 v135, 0
	v_mov_b32_e32 v133, 0
	v_mov_b32_e32 v131, 0
	v_mov_b32_e32 v129, 0
	v_mov_b32_e32 v127, 0
	v_mov_b32_e32 v125, 0
	v_mov_b32_e32 v123, 0
	v_mov_b32_e32 v121, 0
	v_mov_b32_e32 v119, 0
	v_mov_b32_e32 v117, 0
	v_mov_b32_e32 v115, 0
	v_mov_b32_e32 v113, 0
	v_mov_b32_e32 v111, 0
	v_mov_b32_e32 v109, 0
	v_mov_b32_e32 v107, 0
	v_mov_b32_e32 v106, 0
	s_cbranch_scc1 .LBB0_829
	ds_read2st64_b32 v[64:65], v190 offset0:32 offset1:33
	ds_read2st64_b32 v[66:67], v190 offset0:34 offset1:35
	ds_read2st64_b32 v[68:69], v190 offset0:36 offset1:37
	ds_read2st64_b32 v[70:71], v190 offset0:38 offset1:39
	s_waitcnt lgkmcnt(3)
	v_ashrrev_i32_e32 v72, 31, v64
	v_bitop3_b32 v72, v72, v64, s31 bitop3:0x36
	s_waitcnt lgkmcnt(2)
	v_ashrrev_i32_e32 v64, 31, v66
	v_bitop3_b32 v74, v64, v66, s31 bitop3:0x36
	v_ashrrev_i32_e32 v64, 31, v67
	v_bitop3_b32 v75, v64, v67, s31 bitop3:0x36
	s_waitcnt lgkmcnt(1)
	v_ashrrev_i32_e32 v64, 31, v68
	v_bitop3_b32 v76, v64, v68, s31 bitop3:0x36
	v_ashrrev_i32_e32 v64, 31, v69
	v_ashrrev_i32_e32 v73, 31, v65
	v_bitop3_b32 v77, v64, v69, s31 bitop3:0x36
	s_waitcnt lgkmcnt(0)
	v_ashrrev_i32_e32 v64, 31, v70
	v_bitop3_b32 v73, v73, v65, s31 bitop3:0x36
	v_bitop3_b32 v78, v64, v70, s31 bitop3:0x36
	ds_read2st64_b32 v[64:65], v190 offset0:40 offset1:41
	v_ashrrev_i32_e32 v66, 31, v71
	v_bitop3_b32 v79, v66, v71, s31 bitop3:0x36
	ds_read2st64_b32 v[66:67], v190 offset0:42 offset1:43
	ds_read2st64_b32 v[68:69], v190 offset0:44 offset1:45
	ds_read2st64_b32 v[70:71], v190 offset0:46 offset1:47
	s_waitcnt lgkmcnt(3)
	v_ashrrev_i32_e32 v80, 31, v64
	v_bitop3_b32 v80, v80, v64, s31 bitop3:0x36
	v_ashrrev_i32_e32 v64, 31, v65
	v_bitop3_b32 v81, v64, v65, s31 bitop3:0x36
	s_waitcnt lgkmcnt(2)
	v_ashrrev_i32_e32 v64, 31, v66
	v_bitop3_b32 v82, v64, v66, s31 bitop3:0x36
	v_ashrrev_i32_e32 v64, 31, v67
	v_bitop3_b32 v83, v64, v67, s31 bitop3:0x36
	s_waitcnt lgkmcnt(1)
	v_ashrrev_i32_e32 v64, 31, v68
	v_bitop3_b32 v84, v64, v68, s31 bitop3:0x36
	v_ashrrev_i32_e32 v64, 31, v69
	v_bitop3_b32 v85, v64, v69, s31 bitop3:0x36
	s_waitcnt lgkmcnt(0)
	v_ashrrev_i32_e32 v64, 31, v70
	v_bitop3_b32 v86, v64, v70, s31 bitop3:0x36
	ds_read2st64_b32 v[64:65], v190 offset0:48 offset1:49
	v_ashrrev_i32_e32 v66, 31, v71
	v_bitop3_b32 v87, v66, v71, s31 bitop3:0x36
	ds_read2st64_b32 v[66:67], v190 offset0:50 offset1:51
	ds_read2st64_b32 v[68:69], v190 offset0:52 offset1:53
	ds_read2st64_b32 v[70:71], v190 offset0:54 offset1:55
	s_waitcnt lgkmcnt(3)
	v_ashrrev_i32_e32 v88, 31, v64
	v_bitop3_b32 v88, v88, v64, s31 bitop3:0x36
	v_ashrrev_i32_e32 v64, 31, v65
	v_bitop3_b32 v89, v64, v65, s31 bitop3:0x36
	s_waitcnt lgkmcnt(2)
	v_ashrrev_i32_e32 v64, 31, v66
	v_bitop3_b32 v90, v64, v66, s31 bitop3:0x36
	v_ashrrev_i32_e32 v64, 31, v67
	v_bitop3_b32 v91, v64, v67, s31 bitop3:0x36
	s_waitcnt lgkmcnt(1)
	v_ashrrev_i32_e32 v64, 31, v68
	v_bitop3_b32 v92, v64, v68, s31 bitop3:0x36
	v_ashrrev_i32_e32 v64, 31, v69
	v_bitop3_b32 v93, v64, v69, s31 bitop3:0x36
	s_waitcnt lgkmcnt(0)
	v_ashrrev_i32_e32 v64, 31, v70
	v_bitop3_b32 v94, v64, v70, s31 bitop3:0x36
	ds_read2st64_b32 v[64:65], v190 offset0:56 offset1:57
	v_ashrrev_i32_e32 v66, 31, v71
	v_bitop3_b32 v95, v66, v71, s31 bitop3:0x36
	ds_read2st64_b32 v[66:67], v190 offset0:58 offset1:59
	ds_read2st64_b32 v[68:69], v190 offset0:60 offset1:61
	ds_read2st64_b32 v[70:71], v190 offset0:62 offset1:63
	v_perm_b32 v103, v89, v73, s37
	s_waitcnt lgkmcnt(3)
	v_ashrrev_i32_e32 v102, 31, v64
	v_bitop3_b32 v64, v102, v64, s31 bitop3:0x36
	v_ashrrev_i32_e32 v102, 31, v65
	v_bitop3_b32 v65, v102, v65, s31 bitop3:0x36
	s_waitcnt lgkmcnt(2)
	v_ashrrev_i32_e32 v102, 31, v66
	v_bitop3_b32 v66, v102, v66, s31 bitop3:0x36
	v_ashrrev_i32_e32 v102, 31, v67
	v_bitop3_b32 v67, v102, v67, s31 bitop3:0x36
	s_waitcnt lgkmcnt(1)
	v_ashrrev_i32_e32 v102, 31, v68
	v_bitop3_b32 v68, v102, v68, s31 bitop3:0x36
	v_ashrrev_i32_e32 v102, 31, v69
	v_bitop3_b32 v69, v102, v69, s31 bitop3:0x36
	s_waitcnt lgkmcnt(0)
	v_ashrrev_i32_e32 v102, 31, v70
	v_bitop3_b32 v70, v102, v70, s31 bitop3:0x36
	v_ashrrev_i32_e32 v102, 31, v71
	v_bitop3_b32 v71, v102, v71, s31 bitop3:0x36
	v_perm_b32 v73, v89, v73, s36
	v_perm_b32 v89, v90, v74, s37
	v_perm_b32 v74, v90, v74, s36
	v_perm_b32 v90, v91, v75, s37
	v_perm_b32 v75, v91, v75, s36
	v_perm_b32 v91, v92, v76, s37
	v_perm_b32 v106, v65, v81, s37
	v_perm_b32 v65, v65, v81, s36
	v_perm_b32 v81, v66, v82, s37
	v_perm_b32 v66, v66, v82, s36
	v_perm_b32 v82, v67, v83, s37
	v_perm_b32 v67, v67, v83, s36
	v_perm_b32 v83, v68, v84, s37
	v_perm_b32 v102, v88, v72, s36
	v_perm_b32 v76, v92, v76, s36
	v_perm_b32 v92, v93, v77, s37
	v_perm_b32 v77, v93, v77, s36
	v_perm_b32 v93, v94, v78, s37
	v_perm_b32 v78, v94, v78, s36
	v_perm_b32 v94, v95, v79, s37
	v_perm_b32 v79, v95, v79, s36
	v_perm_b32 v95, v64, v80, s36
	v_perm_b32 v68, v68, v84, s36
	v_perm_b32 v84, v69, v85, s37
	v_perm_b32 v69, v69, v85, s36
	v_perm_b32 v85, v70, v86, s37
	v_perm_b32 v70, v70, v86, s36
	v_perm_b32 v86, v71, v87, s37
	v_perm_b32 v71, v71, v87, s36
	v_perm_b32 v64, v64, v80, s37
	v_perm_b32 v72, v88, v72, s37
	v_perm_b32 v88, v81, v89, s38
	v_perm_b32 v81, v81, v89, s39
	v_perm_b32 v89, v82, v90, s38
	v_perm_b32 v82, v82, v90, s39
	v_perm_b32 v90, v83, v91, s38
	v_perm_b32 v80, v64, v72, s38
	v_perm_b32 v83, v83, v91, s39
	v_perm_b32 v91, v84, v92, s38
	v_perm_b32 v84, v84, v92, s39
	v_perm_b32 v92, v85, v93, s38
	v_perm_b32 v85, v85, v93, s39
	v_perm_b32 v93, v86, v94, s38
	v_perm_b32 v86, v86, v94, s39
	v_perm_b32 v94, v95, v102, s38
	v_perm_b32 v95, v95, v102, s39
	v_perm_b32 v102, v65, v73, s38
	v_perm_b32 v65, v65, v73, s39
	v_perm_b32 v73, v66, v74, s38
	v_perm_b32 v66, v66, v74, s39
	v_perm_b32 v74, v67, v75, s38
	v_perm_b32 v67, v67, v75, s39
	v_perm_b32 v75, v68, v76, s38
	v_perm_b32 v68, v68, v76, s39
	v_perm_b32 v76, v69, v77, s38
	v_perm_b32 v69, v69, v77, s39
	v_perm_b32 v77, v70, v78, s38
	v_perm_b32 v70, v70, v78, s39
	v_perm_b32 v78, v71, v79, s38
	v_perm_b32 v71, v71, v79, s39
	v_lshlrev_b32_e32 v79, 4, v90
	v_bfi_b32 v79, s44, v79, v80
	v_lshrrev_b32_e32 v80, 4, v80
	v_perm_b32 v64, v64, v72, s39
	v_perm_b32 v72, v106, v103, s38
	v_bfi_b32 v80, s44, v90, v80
	v_lshlrev_b32_e32 v90, 4, v91
	v_bfi_b32 v90, s44, v90, v72
	v_lshrrev_b32_e32 v72, 4, v72
	v_bfi_b32 v72, s44, v91, v72
	v_lshlrev_b32_e32 v91, 4, v92
	v_bfi_b32 v91, s44, v91, v88
	v_lshrrev_b32_e32 v88, 4, v88
	v_bfi_b32 v88, s44, v92, v88
	v_lshlrev_b32_e32 v92, 4, v93
	v_bfi_b32 v92, s44, v92, v89
	v_lshrrev_b32_e32 v89, 4, v89
	v_bfi_b32 v89, s44, v93, v89
	v_lshlrev_b32_e32 v93, 4, v83
	v_bfi_b32 v93, s44, v93, v64
	v_lshrrev_b32_e32 v64, 4, v64
	v_perm_b32 v87, v106, v103, s39
	v_bfi_b32 v64, s44, v83, v64
	v_lshlrev_b32_e32 v83, 4, v84
	v_bfi_b32 v83, s44, v83, v87
	v_lshrrev_b32_e32 v87, 4, v87
	v_bfi_b32 v84, s44, v84, v87
	v_lshlrev_b32_e32 v87, 4, v85
	v_bfi_b32 v87, s44, v87, v81
	v_lshrrev_b32_e32 v81, 4, v81
	v_bfi_b32 v81, s44, v85, v81
	v_lshlrev_b32_e32 v85, 4, v86
	v_bfi_b32 v85, s44, v85, v82
	v_lshrrev_b32_e32 v82, 4, v82
	v_bfi_b32 v82, s44, v86, v82
	v_lshlrev_b32_e32 v86, 4, v75
	v_bfi_b32 v86, s44, v86, v94
	v_lshrrev_b32_e32 v94, 4, v94
	v_bfi_b32 v75, s44, v75, v94
	v_lshlrev_b32_e32 v94, 4, v76
	v_bfi_b32 v94, s44, v94, v102
	v_lshrrev_b32_e32 v102, 4, v102
	v_bfi_b32 v76, s44, v76, v102
	v_lshlrev_b32_e32 v102, 4, v77
	v_bfi_b32 v102, s44, v102, v73
	v_lshrrev_b32_e32 v73, 4, v73
	v_bfi_b32 v73, s44, v77, v73
	v_lshlrev_b32_e32 v77, 4, v78
	v_bfi_b32 v77, s44, v77, v74
	v_lshrrev_b32_e32 v74, 4, v74
	v_bfi_b32 v74, s44, v78, v74
	v_lshlrev_b32_e32 v78, 4, v68
	v_bfi_b32 v78, s44, v78, v95
	v_lshrrev_b32_e32 v95, 4, v95
	v_bfi_b32 v68, s44, v68, v95
	v_lshlrev_b32_e32 v95, 4, v69
	v_bfi_b32 v95, s44, v95, v65
	v_lshrrev_b32_e32 v65, 4, v65
	v_bfi_b32 v65, s44, v69, v65
	v_lshlrev_b32_e32 v69, 4, v70
	v_bfi_b32 v69, s44, v69, v66
	v_lshrrev_b32_e32 v66, 4, v66
	v_bfi_b32 v66, s44, v70, v66
	v_lshlrev_b32_e32 v70, 4, v71
	v_bfi_b32 v70, s44, v70, v67
	v_lshrrev_b32_e32 v67, 4, v67
	v_bfi_b32 v67, s44, v71, v67
	v_lshlrev_b32_e32 v71, 2, v91
	v_bfi_b32 v71, s45, v71, v79
	v_lshrrev_b32_e32 v79, 2, v79
	v_bfi_b32 v79, s45, v91, v79
	v_lshlrev_b32_e32 v91, 2, v92
	v_bfi_b32 v91, s45, v91, v90
	v_lshrrev_b32_e32 v90, 2, v90
	v_bfi_b32 v90, s45, v92, v90
	v_lshlrev_b32_e32 v92, 2, v88
	v_bfi_b32 v92, s45, v92, v80
	v_lshrrev_b32_e32 v80, 2, v80
	v_bfi_b32 v80, s45, v88, v80
	v_lshlrev_b32_e32 v88, 2, v89
	v_bfi_b32 v88, s45, v88, v72
	v_lshrrev_b32_e32 v72, 2, v72
	v_bfi_b32 v72, s45, v89, v72
	v_lshlrev_b32_e32 v89, 2, v87
	v_bfi_b32 v89, s45, v89, v93
	v_lshrrev_b32_e32 v93, 2, v93
	v_bfi_b32 v87, s45, v87, v93
	v_lshlrev_b32_e32 v93, 2, v85
	v_bfi_b32 v93, s45, v93, v83
	v_lshrrev_b32_e32 v83, 2, v83
	v_bfi_b32 v83, s45, v85, v83
	v_lshlrev_b32_e32 v85, 2, v81
	v_bfi_b32 v85, s45, v85, v64
	v_lshrrev_b32_e32 v64, 2, v64
	v_bfi_b32 v64, s45, v81, v64
	v_lshlrev_b32_e32 v81, 2, v82
	v_bfi_b32 v81, s45, v81, v84
	v_lshrrev_b32_e32 v84, 2, v84
	v_bfi_b32 v82, s45, v82, v84
	v_lshlrev_b32_e32 v84, 2, v102
	v_bfi_b32 v84, s45, v84, v86
	v_lshrrev_b32_e32 v86, 2, v86
	v_bfi_b32 v86, s45, v102, v86
	v_lshlrev_b32_e32 v102, 2, v77
	v_bfi_b32 v102, s45, v102, v94
	v_lshrrev_b32_e32 v94, 2, v94
	v_bfi_b32 v77, s45, v77, v94
	v_lshlrev_b32_e32 v94, 2, v73
	v_bfi_b32 v94, s45, v94, v75
	v_lshrrev_b32_e32 v75, 2, v75
	v_bfi_b32 v73, s45, v73, v75
	v_lshlrev_b32_e32 v75, 2, v74
	v_bfi_b32 v75, s45, v75, v76
	v_lshrrev_b32_e32 v76, 2, v76
	v_bfi_b32 v74, s45, v74, v76
	v_lshlrev_b32_e32 v76, 2, v69
	v_bfi_b32 v76, s45, v76, v78
	v_lshrrev_b32_e32 v78, 2, v78
	v_bfi_b32 v69, s45, v69, v78
	v_lshlrev_b32_e32 v78, 2, v70
	v_bfi_b32 v78, s45, v78, v95
	v_lshrrev_b32_e32 v95, 2, v95
	v_bfi_b32 v70, s45, v70, v95
	v_lshlrev_b32_e32 v95, 2, v66
	v_bfi_b32 v95, s45, v95, v68
	v_lshrrev_b32_e32 v68, 2, v68
	v_bfi_b32 v66, s45, v66, v68
	v_lshlrev_b32_e32 v68, 2, v67
	v_bfi_b32 v68, s45, v68, v65
	v_lshrrev_b32_e32 v65, 2, v65
	v_bfi_b32 v65, s45, v67, v65
	v_lshlrev_b32_e32 v67, 1, v91
	v_bfi_b32 v106, s46, v67, v71
	v_lshrrev_b32_e32 v67, 1, v71
	v_bfi_b32 v107, s47, v67, v91
	v_lshlrev_b32_e32 v67, 1, v90
	v_bfi_b32 v109, s46, v67, v79
	v_lshrrev_b32_e32 v67, 1, v79
	v_bfi_b32 v111, s47, v67, v90
	v_lshlrev_b32_e32 v67, 1, v88
	v_bfi_b32 v113, s46, v67, v92
	v_lshrrev_b32_e32 v67, 1, v92
	v_bfi_b32 v115, s47, v67, v88
	v_lshlrev_b32_e32 v67, 1, v72
	v_bfi_b32 v117, s46, v67, v80
	v_lshrrev_b32_e32 v67, 1, v80
	v_bfi_b32 v119, s47, v67, v72
	v_lshlrev_b32_e32 v67, 1, v93
	v_bfi_b32 v121, s46, v67, v89
	v_lshrrev_b32_e32 v67, 1, v89
	v_bfi_b32 v123, s47, v67, v93
	v_lshlrev_b32_e32 v67, 1, v83
	v_bfi_b32 v125, s46, v67, v87
	v_lshrrev_b32_e32 v67, 1, v87
	v_bfi_b32 v127, s47, v67, v83
	v_lshlrev_b32_e32 v67, 1, v81
	v_bfi_b32 v129, s46, v67, v85
	v_lshrrev_b32_e32 v67, 1, v85
	v_bfi_b32 v131, s47, v67, v81
	v_lshlrev_b32_e32 v67, 1, v82
	v_bfi_b32 v133, s46, v67, v64
	v_lshrrev_b32_e32 v64, 1, v64
	v_bfi_b32 v135, s47, v64, v82
	v_lshlrev_b32_e32 v64, 1, v102
	v_bfi_b32 v137, s46, v64, v84
	v_lshrrev_b32_e32 v64, 1, v84
	v_bfi_b32 v139, s47, v64, v102
	v_lshlrev_b32_e32 v64, 1, v77
	v_bfi_b32 v141, s46, v64, v86
	v_lshrrev_b32_e32 v64, 1, v86
	v_bfi_b32 v143, s47, v64, v77
	v_lshlrev_b32_e32 v64, 1, v75
	v_bfi_b32 v145, s46, v64, v94
	v_lshrrev_b32_e32 v64, 1, v94
	v_bfi_b32 v147, s47, v64, v75
	v_lshlrev_b32_e32 v64, 1, v74
	v_bfi_b32 v149, s46, v64, v73
	v_lshrrev_b32_e32 v64, 1, v73
	v_bfi_b32 v151, s47, v64, v74
	v_lshlrev_b32_e32 v64, 1, v78
	v_bfi_b32 v153, s46, v64, v76
	v_lshrrev_b32_e32 v64, 1, v76
	v_bfi_b32 v155, s47, v64, v78
	v_lshlrev_b32_e32 v64, 1, v70
	v_bfi_b32 v157, s46, v64, v69
	v_lshrrev_b32_e32 v64, 1, v69
	v_bfi_b32 v159, s47, v64, v70
	v_lshlrev_b32_e32 v64, 1, v68
	v_bfi_b32 v161, s46, v64, v95
	v_lshrrev_b32_e32 v64, 1, v95
	v_bfi_b32 v183, s47, v64, v68
	v_lshlrev_b32_e32 v64, 1, v65
	v_bfi_b32 v185, s46, v64, v66
	v_lshrrev_b32_e32 v64, 1, v66
	v_bfi_b32 v186, s47, v64, v65

.LBB0_830:
	s_waitcnt vmcnt(14)
	v_mov_b32_e32 v92, 0
	s_cmpk_lt_u32 s19, 0x1001
	v_mov_b32_e32 v90, 0
	v_mov_b32_e32 v88, 0
	s_waitcnt vmcnt(2)
	v_mov_b32_e32 v86, 0
	v_mov_b32_e32 v84, 0
	v_mov_b32_e32 v82, 0
	v_mov_b32_e32 v80, 0
	v_mov_b32_e32 v78, 0
	v_mov_b32_e32 v76, 0
	v_mov_b32_e32 v74, 0
	v_mov_b32_e32 v72, 0
	v_mov_b32_e32 v70, 0
	v_mov_b32_e32 v68, 0
	v_mov_b32_e32 v66, 0
	v_mov_b32_e32 v64, 0
	v_mov_b32_e32 v62, 0
	v_mov_b32_e32 v60, 0
	v_mov_b32_e32 v58, 0
	v_mov_b32_e32 v56, 0
	s_waitcnt vmcnt(0)
	v_mov_b32_e32 v54, 0
	v_mov_b32_e32 v52, 0
	v_mov_b32_e32 v50, 0
	v_mov_b32_e32 v48, 0
	v_mov_b32_e32 v46, 0
	v_mov_b32_e32 v34, 0
	v_mov_b32_e32 v36, 0
	v_mov_b32_e32 v38, 0
	v_mov_b32_e32 v40, 0
	v_mov_b32_e32 v42, 0
	v_mov_b32_e32 v45, 0
	v_mov_b32_e32 v47, 0
	v_mov_b32_e32 v49, 0
	v_mov_b32_e32 v51, 0
	v_mov_b32_e32 v53, 0
	v_mov_b32_e32 v55, 0
	v_mov_b32_e32 v57, 0
	v_mov_b32_e32 v59, 0
	v_mov_b32_e32 v61, 0
	v_mov_b32_e32 v63, 0
	v_mov_b32_e32 v65, 0
	v_mov_b32_e32 v67, 0
	v_mov_b32_e32 v69, 0
	v_mov_b32_e32 v71, 0
	v_mov_b32_e32 v73, 0
	v_mov_b32_e32 v75, 0
	v_mov_b32_e32 v77, 0
	v_mov_b32_e32 v79, 0
	v_mov_b32_e32 v81, 0
	v_mov_b32_e32 v83, 0
	v_mov_b32_e32 v85, 0
	v_mov_b32_e32 v87, 0
	v_mov_b32_e32 v89, 0
	v_mov_b32_e32 v91, 0
	v_mov_b32_e32 v93, 0
	v_mov_b32_e32 v94, 0
	v_mov_b32_e32 v95, 0
	v_mov_b32_e32 v32, 0
	v_mov_b32_e32 v33, 0
	v_mov_b32_e32 v35, 0
	v_mov_b32_e32 v37, 0
	v_mov_b32_e32 v39, 0
	v_mov_b32_e32 v41, 0
	v_mov_b32_e32 v43, 0
	v_mov_b32_e32 v44, 0
	s_cbranch_scc1 .LBB0_843
	s_min_u32 s6, s19, 0x2000
	s_addk_i32 s6, 0xf01f
	s_lshr_b32 s6, s6, 5
	s_sub_i32 s8, s6, s12
	s_cmp_lt_i32 s8, 1
	s_barrier
	s_cbranch_scc1 .LBB0_840
	s_add_i32 s6, s8, 7
	s_lshr_b32 s7, s6, 29
	s_add_i32 s6, s6, s7
	s_ashr_i32 s6, s6, 3
	s_add_i32 s7, s6, -1
	s_add_i32 s9, s12, 0x80
	s_lshl_b32 s40, s7, 3
	s_cmp_lt_u32 s8, 9
	s_cselect_b32 s57, s40, 8
	s_add_i32 s57, s57, s9
	s_cmp_lt_u32 s8, 17
	s_cselect_b32 s8, s40, 16
	s_add_i32 s8, s8, s9
	v_lshl_or_b32 v102, s9, 5, v191
	v_lshl_or_b32 v40, s57, 5, v191
	v_lshl_or_b32 v48, s8, 5, v191
	v_ashrrev_i32_e32 v103, 31, v102
	v_ashrrev_i32_e32 v41, 31, v40
	v_ashrrev_i32_e32 v49, 31, v48
	v_lshlrev_b64 v[32:33], 7, v[102:103]
	v_lshlrev_b64 v[40:41], 7, v[40:41]
	v_lshlrev_b64 v[48:49], 7, v[48:49]
	v_lshl_add_u64 v[36:37], v[100:101], 0, v[32:33]
	v_lshl_add_u64 v[44:45], v[100:101], 0, v[40:41]
	v_lshl_add_u64 v[52:53], v[100:101], 0, v[48:49]
	s_waitcnt vmcnt(0)
	v_mov_b32_e32 v64, v208
	v_mov_b32_e32 v65, v209
	v_mov_b32_e32 v66, v210
	v_mov_b32_e32 v67, v211
	v_mov_b32_e32 v68, v212
	v_mov_b32_e32 v69, v213
	v_mov_b32_e32 v70, v214
	v_mov_b32_e32 v71, v215
	v_mov_b32_e32 v32, v216
	v_mov_b32_e32 v33, v217
	v_mov_b32_e32 v34, v218
	v_mov_b32_e32 v35, v219
	v_mov_b32_e32 v36, v220
	v_mov_b32_e32 v37, v221
	v_mov_b32_e32 v38, v222
	v_mov_b32_e32 v39, v223
	v_mov_b32_e32 v72, v224
	v_mov_b32_e32 v73, v225
	v_mov_b32_e32 v74, v226
	v_mov_b32_e32 v75, v227
	v_mov_b32_e32 v76, v228
	v_mov_b32_e32 v77, v229
	v_mov_b32_e32 v78, v230
	v_mov_b32_e32 v79, v231
	v_mov_b32_e32 v40, v232
	v_mov_b32_e32 v41, v233
	v_mov_b32_e32 v42, v234
	v_mov_b32_e32 v43, v235
	v_mov_b32_e32 v44, v236
	v_mov_b32_e32 v45, v237
	v_mov_b32_e32 v46, v238
	v_mov_b32_e32 v47, v239
	v_mov_b32_e32 v80, v240
	v_mov_b32_e32 v81, v241
	v_mov_b32_e32 v82, v242
	v_mov_b32_e32 v83, v243
	v_mov_b32_e32 v84, v244
	v_mov_b32_e32 v85, v245
	v_mov_b32_e32 v86, v246
	v_mov_b32_e32 v87, v247
	v_mov_b32_e32 v48, v248
	v_mov_b32_e32 v49, v249
	v_mov_b32_e32 v50, v250
	v_mov_b32_e32 v51, v251
	v_mov_b32_e32 v52, v252
	v_mov_b32_e32 v53, v253
	v_mov_b32_e32 v54, v254
	v_mov_b32_e32 v55, v255
	s_mov_b32 s8, 6
	s_branch .LBB0_834

.LBB0_1141:
	s_waitcnt lgkmcnt(0)
	s_add_i32 s6, s18, s12
	v_lshl_add_u32 v0, v96, 2, s40
	s_ashr_i32 s7, s6, 31
	ds_read_b128 v[0:3], v0
	s_lshl_b64 s[6:7], s[6:7], 10
	s_add_u32 s6, s24, s6
	s_addc_u32 s7, s25, s7
	v_lshl_add_u64 v[4:5], v[96:97], 2, s[6:7]
	s_waitcnt lgkmcnt(0)
	global_store_dwordx4 v[4:5], v[0:3], off
	s_barrier
	s_and_saveexec_b64 s[6:7], s[28:29]
	s_cbranch_execz .LBB0_808
	v_mov_b32_e32 v0, s3
	v_mov_b32_e32 v105, s101
	ds_write_b32 v0, v105
	s_branch .LBB0_808
